# phase 9: the 60 split-K partial loads of rounds 1-15 issued up front with round 0's (prologue de-serialisation)
# speedup vs baseline: 1.0007x; 1.0007x over previous
.LBB0_1106:
	s_andn2_b64 vcc, exec, s[6:7]
	s_cbranch_vccnz .LBB0_1190
	s_lshl_b32 s23, s29, 5
	s_lshl_b32 s22, s3, 2
	s_add_i32 s23, s23, s22
	s_cmpk_gt_u32 s29, 0x7f
	s_cselect_b64 s[8:9], -1, 0
	s_cmpk_lt_u32 s29, 0x80
	s_movk_i32 s6, 0x70
	s_mov_b64 s[4:5], s[0:1]
	s_cselect_b32 s6, s6, 0x80
	s_add_u32 s10, s4, s6
	s_addc_u32 s11, s5, 0
	s_load_dwordx2 s[12:13], s[10:11], 0x0
	s_load_dwordx2 s[6:7], s[4:5], 0xb0
	v_lshlrev_b32_e32 v2, 2, v1
	v_ashrrev_i32_e32 v3, 31, v2
	s_movk_i32 s4, 0x2000
	s_waitcnt lgkmcnt(0)
	v_lshl_add_u64 v[26:27], v[2:3], 2, s[12:13]
	v_add_co_u32_e32 v10, vcc, s4, v26
	s_movk_i32 s4, 0x4000
	s_nop 0
	v_addc_co_u32_e32 v11, vcc, 0, v27, vcc
	v_add_co_u32_e32 v18, vcc, s4, v26
	s_movk_i32 s4, 0x6000
	s_nop 0
	v_addc_co_u32_e32 v19, vcc, 0, v27, vcc
	v_add_co_u32_e32 v20, vcc, s4, v26
	s_mov_b32 s4, 0x8000
	s_nop 0
	v_addc_co_u32_e32 v21, vcc, 0, v27, vcc
	v_add_co_u32_e32 v28, vcc, s4, v26
	s_mov_b32 s4, 0xa000
	s_nop 0
	v_addc_co_u32_e32 v29, vcc, 0, v27, vcc
	v_add_co_u32_e32 v30, vcc, s4, v26
	s_mov_b32 s4, 0xc000
	s_nop 0
	v_addc_co_u32_e32 v31, vcc, 0, v27, vcc
	v_add_co_u32_e32 v34, vcc, s4, v26
	s_mov_b32 s4, 0xe000
	s_nop 0
	v_addc_co_u32_e32 v35, vcc, 0, v27, vcc
	v_add_co_u32_e32 v36, vcc, s4, v26
	s_ashr_i32 s10, s29, 7
	global_load_dwordx4 v[2:5], v[26:27], off
	global_load_dwordx4 v[6:9], v[10:11], off
	s_nop 0
	global_load_dwordx4 v[10:13], v[18:19], off
	global_load_dwordx4 v[14:17], v[20:21], off
	s_nop 0
	global_load_dwordx4 v[18:21], v[28:29], off
	global_load_dwordx4 v[22:25], v[30:31], off
	v_addc_co_u32_e32 v37, vcc, 0, v27, vcc
	global_load_dwordx4 v[26:29], v[34:35], off
	global_load_dwordx4 v[30:33], v[36:37], off
	v_lshl_or_b32 v34, s10, 11, v106
	v_ashrrev_i32_e32 v35, 31, v34
	v_lshl_add_u64 v[34:35], v[34:35], 2, s[6:7]
	s_mov_b64 s[4:5], 0x5d00000
	v_lshl_add_u64 v[36:37], v[34:35], 0, s[4:5]
	s_mov_b32 s4, 0x5d01000
	v_add_co_u32_e32 v34, vcc, s4, v34
	s_bfe_u32 s4, s23, 0x40008
	s_lshl_b32 s5, s10, 4
	s_or_b32 s4, s4, s5
	s_lshl_b32 s5, s23, 9
	s_and_b32 s5, s5, 0x1f800
	s_add_u32 s12, s6, s5
	s_addc_u32 s13, s7, 0
	v_mov_b32_e32 v39, 0
	v_lshlrev_b32_e32 v38, 1, v106
	s_ashr_i32 s5, s4, 31
	v_lshl_add_u64 v[40:41], s[12:13], 0, v[38:39]
	s_lshl_b64 s[4:5], s[4:5], 17
	v_addc_co_u32_e32 v35, vcc, 0, v35, vcc
	v_lshl_add_u64 v[42:43], v[40:41], 0, s[4:5]
	s_mov_b32 s4, 0x4a00000
	v_add_co_u32_e32 v40, vcc, s4, v42
	s_mov_b32 s4, 0x4e00000
	s_nop 0
	v_addc_co_u32_e32 v41, vcc, 0, v43, vcc
	global_load_dword v44, v[34:35], off offset:-4096
	global_load_dword v69, v[34:35], off
	global_load_dword v70, v[34:35], off offset:1024
	global_load_dword v71, v[34:35], off offset:2048
	global_load_dword v72, v[34:35], off offset:3072
	global_load_dword v73, v[36:37], off offset:1024
	global_load_dword v74, v[36:37], off offset:2048
	global_load_dword v62, v[36:37], off offset:256
	global_load_dword v45, v[36:37], off offset:1280
	global_load_dword v55, v[36:37], off offset:512
	global_load_dword v46, v[36:37], off offset:1536
	global_load_dword v47, v[36:37], off offset:1792
	global_load_dword v48, v[36:37], off offset:768
	global_load_dword v39, v[36:37], off offset:3072
	global_load_dword v64, v[36:37], off offset:2304
	global_load_dword v63, v[36:37], off offset:3328
	global_load_dword v57, v[36:37], off offset:2560
	global_load_dword v56, v[36:37], off offset:3584
	global_load_dword v49, v[36:37], off offset:3840
	global_load_ushort v75, v[40:41], off
	global_load_dword v50, v[36:37], off offset:2816
	v_add_co_u32_e32 v36, vcc, s4, v42
	s_mov_b32 s4, 0x5200000
	s_nop 0
	v_addc_co_u32_e32 v37, vcc, 0, v43, vcc
	global_load_ushort v76, v[36:37], off
	v_add_co_u32_e32 v36, vcc, s4, v42
	s_mov_b32 s4, 0x5600000
	s_nop 0
	v_addc_co_u32_e32 v37, vcc, 0, v43, vcc
	v_add_co_u32_e32 v40, vcc, s4, v42
	s_mov_b32 s4, 0x3f200000
	s_nop 0
	v_addc_co_u32_e32 v41, vcc, 0, v43, vcc
	global_load_dword v65, v[34:35], off offset:256
	global_load_ushort v77, v[36:37], off
	global_load_dword v58, v[34:35], off offset:512
	global_load_dword v51, v[34:35], off offset:768
	global_load_ushort v78, v[40:41], off
	global_load_dword v66, v[34:35], off offset:1280
	global_load_dword v67, v[34:35], off offset:2304
	global_load_dword v59, v[34:35], off offset:1536
	global_load_dword v60, v[34:35], off offset:2560
	global_load_dword v52, v[34:35], off offset:2816
	global_load_dword v53, v[34:35], off offset:1792
	global_load_dword v68, v[34:35], off offset:3328
	global_load_dword v61, v[34:35], off offset:3584
	global_load_dword v54, v[34:35], off offset:3840
	s_mov_b64 s[12:13], 0x4a00000
	s_mov_b64 s[14:15], 0x4e00000
	s_mov_b64 s[18:19], 0x5200000
	s_mov_b64 s[16:17], 0x5600000
	v_lshl_add_u64 v[86:87], v[42:43], 0, s[12:13]
	v_lshl_add_u64 v[130:131], v[42:43], 0, s[14:15]
	v_lshl_add_u64 v[132:133], v[42:43], 0, s[18:19]
	v_lshl_add_u64 v[134:135], v[42:43], 0, s[16:17]
	global_load_ushort v107, v[86:87], off offset:128
	global_load_ushort v108, v[130:131], off offset:128
	global_load_ushort v114, v[132:133], off offset:128
	global_load_ushort v115, v[134:135], off offset:128
	global_load_ushort v126, v[86:87], off offset:256
	global_load_ushort v128, v[130:131], off offset:256
	global_load_ushort v136, v[132:133], off offset:256
	global_load_ushort v137, v[134:135], off offset:256
	global_load_ushort v138, v[86:87], off offset:384
	global_load_ushort v139, v[130:131], off offset:384
	global_load_ushort v140, v[132:133], off offset:384
	global_load_ushort v141, v[134:135], off offset:384
	global_load_ushort v142, v[86:87], off offset:512
	global_load_ushort v143, v[130:131], off offset:512
	global_load_ushort v144, v[132:133], off offset:512
	global_load_ushort v145, v[134:135], off offset:512
	global_load_ushort v146, v[86:87], off offset:640
	global_load_ushort v147, v[130:131], off offset:640
	global_load_ushort v206, v[132:133], off offset:640
	global_load_ushort v207, v[134:135], off offset:640
	global_load_ushort v208, v[86:87], off offset:768
	global_load_ushort v209, v[130:131], off offset:768
	global_load_ushort v210, v[132:133], off offset:768
	global_load_ushort v211, v[134:135], off offset:768
	global_load_ushort v212, v[86:87], off offset:896
	global_load_ushort v213, v[130:131], off offset:896
	global_load_ushort v214, v[132:133], off offset:896
	global_load_ushort v215, v[134:135], off offset:896
	global_load_ushort v217, v[86:87], off offset:1024
	global_load_ushort v218, v[130:131], off offset:1024
	global_load_ushort v219, v[132:133], off offset:1024
	global_load_ushort v220, v[134:135], off offset:1024
	global_load_ushort v221, v[86:87], off offset:1152
	global_load_ushort v222, v[130:131], off offset:1152
	global_load_ushort v223, v[132:133], off offset:1152
	global_load_ushort v224, v[134:135], off offset:1152
	global_load_ushort v225, v[86:87], off offset:1280
	global_load_ushort v226, v[130:131], off offset:1280
	global_load_ushort v227, v[132:133], off offset:1280
	global_load_ushort v228, v[134:135], off offset:1280
	global_load_ushort v229, v[86:87], off offset:1408
	global_load_ushort v230, v[130:131], off offset:1408
	global_load_ushort v231, v[132:133], off offset:1408
	global_load_ushort v232, v[134:135], off offset:1408
	global_load_ushort v233, v[86:87], off offset:1536
	global_load_ushort v234, v[130:131], off offset:1536
	global_load_ushort v235, v[132:133], off offset:1536
	global_load_ushort v236, v[134:135], off offset:1536
	global_load_ushort v237, v[86:87], off offset:1664
	global_load_ushort v238, v[130:131], off offset:1664
	global_load_ushort v239, v[132:133], off offset:1664
	global_load_ushort v240, v[134:135], off offset:1664
	global_load_ushort v241, v[86:87], off offset:1792
	global_load_ushort v242, v[130:131], off offset:1792
	global_load_ushort v243, v[132:133], off offset:1792
	global_load_ushort v244, v[134:135], off offset:1792
	global_load_ushort v245, v[86:87], off offset:1920
	global_load_ushort v246, v[130:131], off offset:1920
	global_load_ushort v247, v[132:133], off offset:1920
	global_load_ushort v248, v[134:135], off offset:1920
	s_waitcnt vmcnt(0)
	v_add_f32_e32 v34, 0, v44
	v_add_f32_e32 v34, v34, v73
	v_add_f32_e32 v34, v34, v74
	v_add_f32_e32 v34, v34, v39
	v_add_f32_e32 v34, v34, v69
	v_add_f32_e32 v34, v34, v70
	v_add_f32_e32 v34, v34, v71
	v_add_f32_e32 v44, v34, v72
	v_lshlrev_b32_e32 v34, 16, v75
	v_add_f32_e32 v34, v44, v34
	v_lshlrev_b32_e32 v35, 16, v76
	v_add_f32_e32 v34, v34, v35
	v_lshlrev_b32_e32 v35, 16, v77
	v_add_f32_e32 v34, v34, v35
	v_lshlrev_b32_e32 v35, 16, v78
	v_add_f32_e32 v39, v34, v35
	v_mul_f32_e32 v34, 0x3d372713, v39
	v_mul_f32_e32 v34, v39, v34
	v_fma_f32 v34, v39, v34, v39
	v_mul_f32_e32 v69, 0x3f4c422a, v34
	v_cmp_nlt_f32_e64 s[4:5], |v69|, s4
	s_and_saveexec_b64 s[20:21], s[4:5]
	s_xor_b64 s[20:21], exec, s[20:21]
	s_cbranch_execz .LBB0_1109
	v_add_f32_e64 v34, |v69|, |v69|
	v_mul_f32_e32 v35, 0x3fb8aa3b, v34
	s_mov_b32 s4, 0x3fb8aa3b
	v_rndne_f32_e32 v36, v35
	v_sub_f32_e32 v37, v35, v36
	v_fma_f32 v35, v34, s4, -v35
	v_fmamk_f32 v35, v34, 0x32a5705f, v35
	v_add_f32_e32 v35, v37, v35
	v_exp_f32_e32 v35, v35
	v_cvt_i32_f32_e32 v36, v36
	s_mov_b32 s4, 0xc2ce8ed0
	v_cmp_ngt_f32_e32 vcc, s4, v34
	s_mov_b32 s4, 0x42b17218
	v_ldexp_f32 v35, v35, v36
	v_cndmask_b32_e32 v35, 0, v35, vcc
	v_mov_b32_e32 v36, 0x7f800000
	v_cmp_nlt_f32_e32 vcc, s4, v34
	s_nop 1
	v_cndmask_b32_e32 v34, v36, v35, vcc
	v_add_f32_e32 v34, 1.0, v34
	v_rcp_f32_e32 v34, v34
	s_nop 0
	v_fma_f32 v70, v34, -2.0, 1.0
.LBB0_1109:
	s_or_saveexec_b64 s[20:21], s[20:21]
	v_lshl_add_u64 v[40:41], v[42:43], 0, s[12:13]
	v_lshl_add_u64 v[34:35], v[42:43], 0, s[14:15]
	v_lshl_add_u64 v[36:37], v[42:43], 0, s[18:19]
	v_lshl_add_u64 v[42:43], v[42:43], 0, s[16:17]
	s_xor_b64 exec, exec, s[20:21]
	v_mul_f32_e32 v70, v69, v69
	v_mov_b32_e32 v71, 0x3ca908c9
	v_fmac_f32_e32 v71, 0xbbbac73d, v70
	v_fmaak_f32 v71, v70, v71, 0xbd5c1c4e
	v_fmaak_f32 v71, v70, v71, 0x3e088382
	v_fmaak_f32 v71, v70, v71, 0xbeaaaa99
	v_mul_f32_e64 v71, |v69|, v71
	v_fma_f32 v70, v70, v71, |v69|
	s_or_b64 exec, exec, s[20:21]
	v_add_f32_e32 v62, 0, v62
	v_add_f32_e32 v45, v62, v45
	v_add_f32_e32 v45, v45, v64
	s_brev_b32 s4, -2
	v_add_f32_e32 v45, v45, v63
	v_bfi_b32 v62, s4, v70, v69
	v_add_f32_e32 v45, v45, v65
	s_add_i32 s11, s28, 0
	v_mul_f32_e32 v75, 0.5, v39
	v_add_f32_e32 v62, 1.0, v62
	v_add_f32_e32 v45, v45, v66
	v_lshl_add_u32 v39, v106, 2, s11
	v_mul_f32_e32 v62, v75, v62
	v_add_f32_e32 v45, v45, v67
	ds_write_b32 v39, v62
	v_add_f32_e32 v45, v45, v68
	s_mov_b32 s4, 0x3f200000
	s_waitcnt vmcnt(3)
	v_lshlrev_b32_e32 v62, 16, v107
	s_waitcnt vmcnt(2)
	v_lshlrev_b32_e32 v63, 16, v108
	v_add_f32_e32 v62, v45, v62
	s_waitcnt vmcnt(1)
	v_lshlrev_b32_e32 v64, 16, v114
	v_add_f32_e32 v62, v62, v63
	s_waitcnt vmcnt(0)
	v_lshlrev_b32_e32 v65, 16, v115
	v_add_f32_e32 v62, v62, v64
	v_add_f32_e32 v62, v62, v65
	v_mul_f32_e32 v63, 0x3d372713, v62
	v_mul_f32_e32 v63, v62, v63
	v_fma_f32 v63, v62, v63, v62
	v_mul_f32_e32 v63, 0x3f4c422a, v63
	v_cmp_nlt_f32_e64 s[4:5], |v63|, s4
	s_and_saveexec_b64 s[12:13], s[4:5]
	s_xor_b64 s[12:13], exec, s[12:13]
	s_cbranch_execz .LBB0_1113
	v_add_f32_e64 v64, |v63|, |v63|
	v_mul_f32_e32 v65, 0x3fb8aa3b, v64
	s_mov_b32 s4, 0x3fb8aa3b
	v_rndne_f32_e32 v66, v65
	v_sub_f32_e32 v67, v65, v66
	v_fma_f32 v65, v64, s4, -v65
	v_fmamk_f32 v65, v64, 0x32a5705f, v65
	v_add_f32_e32 v65, v67, v65
	v_exp_f32_e32 v65, v65
	v_cvt_i32_f32_e32 v66, v66
	s_mov_b32 s4, 0xc2ce8ed0
	v_cmp_ngt_f32_e32 vcc, s4, v64
	s_mov_b32 s4, 0x42b17218
	v_ldexp_f32 v65, v65, v66
	v_cndmask_b32_e32 v65, 0, v65, vcc
	v_mov_b32_e32 v66, 0x7f800000
	v_cmp_nlt_f32_e32 vcc, s4, v64
	s_nop 1
	v_cndmask_b32_e32 v64, v66, v65, vcc
	v_add_f32_e32 v64, 1.0, v64
	v_rcp_f32_e32 v64, v64
	s_nop 0
	v_fma_f32 v64, v64, -2.0, 1.0
.LBB0_1113:
	s_andn2_saveexec_b64 s[12:13], s[12:13]
	v_mul_f32_e32 v64, v63, v63
	v_mov_b32_e32 v65, 0x3ca908c9
	v_fmac_f32_e32 v65, 0xbbbac73d, v64
	v_fmaak_f32 v65, v64, v65, 0xbd5c1c4e
	v_fmaak_f32 v65, v64, v65, 0x3e088382
	v_fmaak_f32 v65, v64, v65, 0xbeaaaa99
	v_mul_f32_e64 v65, |v63|, v65
	v_fma_f32 v64, v64, v65, |v63|
	s_or_b64 exec, exec, s[12:13]
	v_add_f32_e32 v55, 0, v55
	v_add_f32_e32 v46, v55, v46
	v_add_f32_e32 v46, v46, v57
	s_brev_b32 s4, -2
	v_add_f32_e32 v46, v46, v56
	v_bfi_b32 v55, s4, v64, v63
	v_add_f32_e32 v46, v46, v58
	v_mul_f32_e32 v62, 0.5, v62
	v_add_f32_e32 v55, 1.0, v55
	v_add_f32_e32 v46, v46, v59
	v_mul_f32_e32 v55, v62, v55
	v_add_f32_e32 v46, v46, v60
	ds_write_b32 v39, v55 offset:256
	v_add_f32_e32 v46, v46, v61
	s_mov_b32 s4, 0x3f200000
	s_waitcnt vmcnt(3)
	v_lshlrev_b32_e32 v55, 16, v126
	s_waitcnt vmcnt(2)
	v_lshlrev_b32_e32 v56, 16, v128
	v_add_f32_e32 v55, v46, v55
	s_waitcnt vmcnt(1)
	v_lshlrev_b32_e32 v57, 16, v136
	v_add_f32_e32 v55, v55, v56
	s_waitcnt vmcnt(0)
	v_lshlrev_b32_e32 v58, 16, v137
	v_add_f32_e32 v55, v55, v57
	v_add_f32_e32 v55, v55, v58
	v_mul_f32_e32 v56, 0x3d372713, v55
	v_mul_f32_e32 v56, v55, v56
	v_fma_f32 v56, v55, v56, v55
	v_mul_f32_e32 v56, 0x3f4c422a, v56
	v_cmp_nlt_f32_e64 s[4:5], |v56|, s4
	s_and_saveexec_b64 s[12:13], s[4:5]
	s_xor_b64 s[12:13], exec, s[12:13]
	s_cbranch_execz .LBB0_1117
	v_add_f32_e64 v57, |v56|, |v56|
	v_mul_f32_e32 v58, 0x3fb8aa3b, v57
	s_mov_b32 s4, 0x3fb8aa3b
	v_rndne_f32_e32 v59, v58
	v_sub_f32_e32 v60, v58, v59
	v_fma_f32 v58, v57, s4, -v58
	v_fmamk_f32 v58, v57, 0x32a5705f, v58
	v_add_f32_e32 v58, v60, v58
	v_exp_f32_e32 v58, v58
	v_cvt_i32_f32_e32 v59, v59
	s_mov_b32 s4, 0xc2ce8ed0
	v_cmp_ngt_f32_e32 vcc, s4, v57
	s_mov_b32 s4, 0x42b17218
	v_ldexp_f32 v58, v58, v59
	v_cndmask_b32_e32 v58, 0, v58, vcc
	v_mov_b32_e32 v59, 0x7f800000
	v_cmp_nlt_f32_e32 vcc, s4, v57
	s_nop 1
	v_cndmask_b32_e32 v57, v59, v58, vcc
	v_add_f32_e32 v57, 1.0, v57
	v_rcp_f32_e32 v57, v57
	s_nop 0
	v_fma_f32 v57, v57, -2.0, 1.0
.LBB0_1117:
	s_andn2_saveexec_b64 s[12:13], s[12:13]
	v_mul_f32_e32 v57, v56, v56
	v_mov_b32_e32 v58, 0x3ca908c9
	v_fmac_f32_e32 v58, 0xbbbac73d, v57
	v_fmaak_f32 v58, v57, v58, 0xbd5c1c4e
	v_fmaak_f32 v58, v57, v58, 0x3e088382
	v_fmaak_f32 v58, v57, v58, 0xbeaaaa99
	v_mul_f32_e64 v58, |v56|, v58
	v_fma_f32 v57, v57, v58, |v56|
	s_or_b64 exec, exec, s[12:13]
	v_add_f32_e32 v48, 0, v48
	v_add_f32_e32 v47, v48, v47
	v_add_f32_e32 v47, v47, v50
	s_brev_b32 s4, -2
	v_add_f32_e32 v47, v47, v49
	v_bfi_b32 v48, s4, v57, v56
	v_add_f32_e32 v47, v47, v51
	v_mul_f32_e32 v55, 0.5, v55
	v_add_f32_e32 v48, 1.0, v48
	v_add_f32_e32 v47, v47, v53
	v_mul_f32_e32 v48, v55, v48
	v_add_f32_e32 v47, v47, v52
	ds_write_b32 v39, v48 offset:512
	v_add_f32_e32 v47, v47, v54
	s_mov_b32 s4, 0x3f200000
	s_waitcnt vmcnt(3)
	v_lshlrev_b32_e32 v48, 16, v138
	s_waitcnt vmcnt(2)
	v_lshlrev_b32_e32 v49, 16, v139
	v_add_f32_e32 v48, v47, v48
	s_waitcnt vmcnt(1)
	v_lshlrev_b32_e32 v50, 16, v140
	v_add_f32_e32 v48, v48, v49
	s_waitcnt vmcnt(0)
	v_lshlrev_b32_e32 v51, 16, v141
	v_add_f32_e32 v48, v48, v50
	v_add_f32_e32 v48, v48, v51
	v_mul_f32_e32 v49, 0x3d372713, v48
	v_mul_f32_e32 v49, v48, v49
	v_fma_f32 v49, v48, v49, v48
	v_mul_f32_e32 v49, 0x3f4c422a, v49
	v_cmp_nlt_f32_e64 s[4:5], |v49|, s4
	s_and_saveexec_b64 s[12:13], s[4:5]
	s_xor_b64 s[12:13], exec, s[12:13]
	s_cbranch_execz .LBB0_1121
	v_add_f32_e64 v50, |v49|, |v49|
	v_mul_f32_e32 v51, 0x3fb8aa3b, v50
	s_mov_b32 s4, 0x3fb8aa3b
	v_rndne_f32_e32 v52, v51
	v_sub_f32_e32 v53, v51, v52
	v_fma_f32 v51, v50, s4, -v51
	v_fmamk_f32 v51, v50, 0x32a5705f, v51
	v_add_f32_e32 v51, v53, v51
	v_exp_f32_e32 v51, v51
	v_cvt_i32_f32_e32 v52, v52
	s_mov_b32 s4, 0xc2ce8ed0
	v_cmp_ngt_f32_e32 vcc, s4, v50
	s_mov_b32 s4, 0x42b17218
	v_ldexp_f32 v51, v51, v52
	v_cndmask_b32_e32 v51, 0, v51, vcc
	v_mov_b32_e32 v52, 0x7f800000
	v_cmp_nlt_f32_e32 vcc, s4, v50
	s_nop 1
	v_cndmask_b32_e32 v50, v52, v51, vcc
	v_add_f32_e32 v50, 1.0, v50
	v_rcp_f32_e32 v50, v50
	s_nop 0
	v_fma_f32 v50, v50, -2.0, 1.0
.LBB0_1121:
	s_andn2_saveexec_b64 s[12:13], s[12:13]
	v_mul_f32_e32 v50, v49, v49
	v_mov_b32_e32 v51, 0x3ca908c9
	v_fmac_f32_e32 v51, 0xbbbac73d, v50
	v_fmaak_f32 v51, v50, v51, 0xbd5c1c4e
	v_fmaak_f32 v51, v50, v51, 0x3e088382
	v_fmaak_f32 v51, v50, v51, 0xbeaaaa99
	v_mul_f32_e64 v51, |v49|, v51
	v_fma_f32 v50, v50, v51, |v49|
	s_or_b64 exec, exec, s[12:13]
	s_brev_b32 s4, -2
	v_bfi_b32 v49, s4, v50, v49
	v_mul_f32_e32 v48, 0.5, v48
	v_add_f32_e32 v49, 1.0, v49
	v_mul_f32_e32 v48, v48, v49
	ds_write_b32 v39, v48 offset:768
	s_mov_b32 s4, 0x3f200000
	s_waitcnt vmcnt(3)
	v_lshlrev_b32_e32 v48, 16, v142
	s_waitcnt vmcnt(2)
	v_lshlrev_b32_e32 v49, 16, v143
	v_add_f32_e32 v48, v44, v48
	s_waitcnt vmcnt(1)
	v_lshlrev_b32_e32 v50, 16, v144
	v_add_f32_e32 v48, v48, v49
	s_waitcnt vmcnt(0)
	v_lshlrev_b32_e32 v51, 16, v145
	v_add_f32_e32 v48, v48, v50
	v_add_f32_e32 v48, v48, v51
	v_mul_f32_e32 v49, 0x3d372713, v48
	v_mul_f32_e32 v49, v48, v49
	v_fma_f32 v49, v48, v49, v48
	v_mul_f32_e32 v49, 0x3f4c422a, v49
	v_cmp_nlt_f32_e64 s[4:5], |v49|, s4
	s_and_saveexec_b64 s[12:13], s[4:5]
	s_xor_b64 s[12:13], exec, s[12:13]
	s_cbranch_execz .LBB0_1125
	v_add_f32_e64 v50, |v49|, |v49|
	v_mul_f32_e32 v51, 0x3fb8aa3b, v50
	s_mov_b32 s4, 0x3fb8aa3b
	v_rndne_f32_e32 v52, v51
	v_sub_f32_e32 v53, v51, v52
	v_fma_f32 v51, v50, s4, -v51
	v_fmamk_f32 v51, v50, 0x32a5705f, v51
	v_add_f32_e32 v51, v53, v51
	v_exp_f32_e32 v51, v51
	v_cvt_i32_f32_e32 v52, v52
	s_mov_b32 s4, 0xc2ce8ed0
	v_cmp_ngt_f32_e32 vcc, s4, v50
	s_mov_b32 s4, 0x42b17218
	v_ldexp_f32 v51, v51, v52
	v_cndmask_b32_e32 v51, 0, v51, vcc
	v_mov_b32_e32 v52, 0x7f800000
	v_cmp_nlt_f32_e32 vcc, s4, v50
	s_nop 1
	v_cndmask_b32_e32 v50, v52, v51, vcc
	v_add_f32_e32 v50, 1.0, v50
	v_rcp_f32_e32 v50, v50
	s_nop 0
	v_fma_f32 v50, v50, -2.0, 1.0
.LBB0_1125:
	s_andn2_saveexec_b64 s[12:13], s[12:13]
	v_mul_f32_e32 v50, v49, v49
	v_mov_b32_e32 v51, 0x3ca908c9
	v_fmac_f32_e32 v51, 0xbbbac73d, v50
	v_fmaak_f32 v51, v50, v51, 0xbd5c1c4e
	v_fmaak_f32 v51, v50, v51, 0x3e088382
	v_fmaak_f32 v51, v50, v51, 0xbeaaaa99
	v_mul_f32_e64 v51, |v49|, v51
	v_fma_f32 v50, v50, v51, |v49|
	s_or_b64 exec, exec, s[12:13]
	s_brev_b32 s4, -2
	v_bfi_b32 v49, s4, v50, v49
	v_mul_f32_e32 v48, 0.5, v48
	v_add_f32_e32 v49, 1.0, v49
	v_mul_f32_e32 v48, v48, v49
	ds_write_b32 v39, v48 offset:1024
	s_mov_b32 s4, 0x3f200000
	s_waitcnt vmcnt(3)
	v_lshlrev_b32_e32 v48, 16, v146
	s_waitcnt vmcnt(2)
	v_lshlrev_b32_e32 v49, 16, v147
	v_add_f32_e32 v48, v45, v48
	s_waitcnt vmcnt(1)
	v_lshlrev_b32_e32 v50, 16, v206
	v_add_f32_e32 v48, v48, v49
	s_waitcnt vmcnt(0)
	v_lshlrev_b32_e32 v51, 16, v207
	v_add_f32_e32 v48, v48, v50
	v_add_f32_e32 v48, v48, v51
	v_mul_f32_e32 v49, 0x3d372713, v48
	v_mul_f32_e32 v49, v48, v49
	v_fma_f32 v49, v48, v49, v48
	v_mul_f32_e32 v49, 0x3f4c422a, v49
	v_cmp_nlt_f32_e64 s[4:5], |v49|, s4
	s_and_saveexec_b64 s[12:13], s[4:5]
	s_xor_b64 s[12:13], exec, s[12:13]
	s_cbranch_execz .LBB0_1129
	v_add_f32_e64 v50, |v49|, |v49|
	v_mul_f32_e32 v51, 0x3fb8aa3b, v50
	s_mov_b32 s4, 0x3fb8aa3b
	v_rndne_f32_e32 v52, v51
	v_sub_f32_e32 v53, v51, v52
	v_fma_f32 v51, v50, s4, -v51
	v_fmamk_f32 v51, v50, 0x32a5705f, v51
	v_add_f32_e32 v51, v53, v51
	v_exp_f32_e32 v51, v51
	v_cvt_i32_f32_e32 v52, v52
	s_mov_b32 s4, 0xc2ce8ed0
	v_cmp_ngt_f32_e32 vcc, s4, v50
	s_mov_b32 s4, 0x42b17218
	v_ldexp_f32 v51, v51, v52
	v_cndmask_b32_e32 v51, 0, v51, vcc
	v_mov_b32_e32 v52, 0x7f800000
	v_cmp_nlt_f32_e32 vcc, s4, v50
	s_nop 1
	v_cndmask_b32_e32 v50, v52, v51, vcc
	v_add_f32_e32 v50, 1.0, v50
	v_rcp_f32_e32 v50, v50
	s_nop 0
	v_fma_f32 v50, v50, -2.0, 1.0
.LBB0_1129:
	s_andn2_saveexec_b64 s[12:13], s[12:13]
	v_mul_f32_e32 v50, v49, v49
	v_mov_b32_e32 v51, 0x3ca908c9
	v_fmac_f32_e32 v51, 0xbbbac73d, v50
	v_fmaak_f32 v51, v50, v51, 0xbd5c1c4e
	v_fmaak_f32 v51, v50, v51, 0x3e088382
	v_fmaak_f32 v51, v50, v51, 0xbeaaaa99
	v_mul_f32_e64 v51, |v49|, v51
	v_fma_f32 v50, v50, v51, |v49|
	s_or_b64 exec, exec, s[12:13]
	s_brev_b32 s4, -2
	v_bfi_b32 v49, s4, v50, v49
	v_mul_f32_e32 v48, 0.5, v48
	v_add_f32_e32 v49, 1.0, v49
	v_mul_f32_e32 v48, v48, v49
	ds_write_b32 v39, v48 offset:1280
	s_mov_b32 s4, 0x3f200000
	s_waitcnt vmcnt(3)
	v_lshlrev_b32_e32 v48, 16, v208
	s_waitcnt vmcnt(2)
	v_lshlrev_b32_e32 v49, 16, v209
	v_add_f32_e32 v48, v46, v48
	s_waitcnt vmcnt(1)
	v_lshlrev_b32_e32 v50, 16, v210
	v_add_f32_e32 v48, v48, v49
	s_waitcnt vmcnt(0)
	v_lshlrev_b32_e32 v51, 16, v211
	v_add_f32_e32 v48, v48, v50
	v_add_f32_e32 v48, v48, v51
	v_mul_f32_e32 v49, 0x3d372713, v48
	v_mul_f32_e32 v49, v48, v49
	v_fma_f32 v49, v48, v49, v48
	v_mul_f32_e32 v49, 0x3f4c422a, v49
	v_cmp_nlt_f32_e64 s[4:5], |v49|, s4
	s_and_saveexec_b64 s[12:13], s[4:5]
	s_xor_b64 s[12:13], exec, s[12:13]
	s_cbranch_execz .LBB0_1133
	v_add_f32_e64 v50, |v49|, |v49|
	v_mul_f32_e32 v51, 0x3fb8aa3b, v50
	s_mov_b32 s4, 0x3fb8aa3b
	v_rndne_f32_e32 v52, v51
	v_sub_f32_e32 v53, v51, v52
	v_fma_f32 v51, v50, s4, -v51
	v_fmamk_f32 v51, v50, 0x32a5705f, v51
	v_add_f32_e32 v51, v53, v51
	v_exp_f32_e32 v51, v51
	v_cvt_i32_f32_e32 v52, v52
	s_mov_b32 s4, 0xc2ce8ed0
	v_cmp_ngt_f32_e32 vcc, s4, v50
	s_mov_b32 s4, 0x42b17218
	v_ldexp_f32 v51, v51, v52
	v_cndmask_b32_e32 v51, 0, v51, vcc
	v_mov_b32_e32 v52, 0x7f800000
	v_cmp_nlt_f32_e32 vcc, s4, v50
	s_nop 1
	v_cndmask_b32_e32 v50, v52, v51, vcc
	v_add_f32_e32 v50, 1.0, v50
	v_rcp_f32_e32 v50, v50
	s_nop 0
	v_fma_f32 v50, v50, -2.0, 1.0
.LBB0_1133:
	s_andn2_saveexec_b64 s[12:13], s[12:13]
	v_mul_f32_e32 v50, v49, v49
	v_mov_b32_e32 v51, 0x3ca908c9
	v_fmac_f32_e32 v51, 0xbbbac73d, v50
	v_fmaak_f32 v51, v50, v51, 0xbd5c1c4e
	v_fmaak_f32 v51, v50, v51, 0x3e088382
	v_fmaak_f32 v51, v50, v51, 0xbeaaaa99
	v_mul_f32_e64 v51, |v49|, v51
	v_fma_f32 v50, v50, v51, |v49|
	s_or_b64 exec, exec, s[12:13]
	s_brev_b32 s4, -2
	v_bfi_b32 v49, s4, v50, v49
	v_mul_f32_e32 v48, 0.5, v48
	v_add_f32_e32 v49, 1.0, v49
	v_mul_f32_e32 v48, v48, v49
	ds_write_b32 v39, v48 offset:1536
	s_mov_b32 s4, 0x3f200000
	s_waitcnt vmcnt(3)
	v_lshlrev_b32_e32 v48, 16, v212
	s_waitcnt vmcnt(2)
	v_lshlrev_b32_e32 v49, 16, v213
	v_add_f32_e32 v48, v47, v48
	s_waitcnt vmcnt(1)
	v_lshlrev_b32_e32 v50, 16, v214
	v_add_f32_e32 v48, v48, v49
	s_waitcnt vmcnt(0)
	v_lshlrev_b32_e32 v51, 16, v215
	v_add_f32_e32 v48, v48, v50
	v_add_f32_e32 v48, v48, v51
	v_mul_f32_e32 v49, 0x3d372713, v48
	v_mul_f32_e32 v49, v48, v49
	v_fma_f32 v49, v48, v49, v48
	v_mul_f32_e32 v49, 0x3f4c422a, v49
	v_cmp_nlt_f32_e64 s[4:5], |v49|, s4
	s_and_saveexec_b64 s[12:13], s[4:5]
	s_xor_b64 s[12:13], exec, s[12:13]
	s_cbranch_execz .LBB0_1137
	v_add_f32_e64 v50, |v49|, |v49|
	v_mul_f32_e32 v51, 0x3fb8aa3b, v50
	s_mov_b32 s4, 0x3fb8aa3b
	v_rndne_f32_e32 v52, v51
	v_sub_f32_e32 v53, v51, v52
	v_fma_f32 v51, v50, s4, -v51
	v_fmamk_f32 v51, v50, 0x32a5705f, v51
	v_add_f32_e32 v51, v53, v51
	v_exp_f32_e32 v51, v51
	v_cvt_i32_f32_e32 v52, v52
	s_mov_b32 s4, 0xc2ce8ed0
	v_cmp_ngt_f32_e32 vcc, s4, v50
	s_mov_b32 s4, 0x42b17218
	v_ldexp_f32 v51, v51, v52
	v_cndmask_b32_e32 v51, 0, v51, vcc
	v_mov_b32_e32 v52, 0x7f800000
	v_cmp_nlt_f32_e32 vcc, s4, v50
	s_nop 1
	v_cndmask_b32_e32 v50, v52, v51, vcc
	v_add_f32_e32 v50, 1.0, v50
	v_rcp_f32_e32 v50, v50
	s_nop 0
	v_fma_f32 v50, v50, -2.0, 1.0
.LBB0_1137:
	s_andn2_saveexec_b64 s[12:13], s[12:13]
	v_mul_f32_e32 v50, v49, v49
	v_mov_b32_e32 v51, 0x3ca908c9
	v_fmac_f32_e32 v51, 0xbbbac73d, v50
	v_fmaak_f32 v51, v50, v51, 0xbd5c1c4e
	v_fmaak_f32 v51, v50, v51, 0x3e088382
	v_fmaak_f32 v51, v50, v51, 0xbeaaaa99
	v_mul_f32_e64 v51, |v49|, v51
	v_fma_f32 v50, v50, v51, |v49|
	s_or_b64 exec, exec, s[12:13]
	s_brev_b32 s4, -2
	v_bfi_b32 v49, s4, v50, v49
	v_mul_f32_e32 v48, 0.5, v48
	v_add_f32_e32 v49, 1.0, v49
	v_mul_f32_e32 v48, v48, v49
	ds_write_b32 v39, v48 offset:1792
	s_mov_b32 s4, 0x3f200000
	s_waitcnt vmcnt(3)
	v_lshlrev_b32_e32 v48, 16, v217
	s_waitcnt vmcnt(2)
	v_lshlrev_b32_e32 v49, 16, v218
	v_add_f32_e32 v48, v44, v48
	s_waitcnt vmcnt(1)
	v_lshlrev_b32_e32 v50, 16, v219
	v_add_f32_e32 v48, v48, v49
	s_waitcnt vmcnt(0)
	v_lshlrev_b32_e32 v51, 16, v220
	v_add_f32_e32 v48, v48, v50
	v_add_f32_e32 v48, v48, v51
	v_mul_f32_e32 v49, 0x3d372713, v48
	v_mul_f32_e32 v49, v48, v49
	v_fma_f32 v49, v48, v49, v48
	v_mul_f32_e32 v49, 0x3f4c422a, v49
	v_cmp_nlt_f32_e64 s[4:5], |v49|, s4
	s_and_saveexec_b64 s[12:13], s[4:5]
	s_xor_b64 s[12:13], exec, s[12:13]
	s_cbranch_execz .LBB0_1141
	v_add_f32_e64 v50, |v49|, |v49|
	v_mul_f32_e32 v51, 0x3fb8aa3b, v50
	s_mov_b32 s4, 0x3fb8aa3b
	v_rndne_f32_e32 v52, v51
	v_sub_f32_e32 v53, v51, v52
	v_fma_f32 v51, v50, s4, -v51
	v_fmamk_f32 v51, v50, 0x32a5705f, v51
	v_add_f32_e32 v51, v53, v51
	v_exp_f32_e32 v51, v51
	v_cvt_i32_f32_e32 v52, v52
	s_mov_b32 s4, 0xc2ce8ed0
	v_cmp_ngt_f32_e32 vcc, s4, v50
	s_mov_b32 s4, 0x42b17218
	v_ldexp_f32 v51, v51, v52
	v_cndmask_b32_e32 v51, 0, v51, vcc
	v_mov_b32_e32 v52, 0x7f800000
	v_cmp_nlt_f32_e32 vcc, s4, v50
	s_nop 1
	v_cndmask_b32_e32 v50, v52, v51, vcc
	v_add_f32_e32 v50, 1.0, v50
	v_rcp_f32_e32 v50, v50
	s_nop 0
	v_fma_f32 v50, v50, -2.0, 1.0
.LBB0_1141:
	s_andn2_saveexec_b64 s[12:13], s[12:13]
	v_mul_f32_e32 v50, v49, v49
	v_mov_b32_e32 v51, 0x3ca908c9
	v_fmac_f32_e32 v51, 0xbbbac73d, v50
	v_fmaak_f32 v51, v50, v51, 0xbd5c1c4e
	v_fmaak_f32 v51, v50, v51, 0x3e088382
	v_fmaak_f32 v51, v50, v51, 0xbeaaaa99
	v_mul_f32_e64 v51, |v49|, v51
	v_fma_f32 v50, v50, v51, |v49|
	s_or_b64 exec, exec, s[12:13]
	s_brev_b32 s4, -2
	v_bfi_b32 v49, s4, v50, v49
	v_mul_f32_e32 v48, 0.5, v48
	v_add_f32_e32 v49, 1.0, v49
	v_mul_f32_e32 v48, v48, v49
	ds_write_b32 v39, v48 offset:2048
	s_mov_b32 s4, 0x3f200000
	s_waitcnt vmcnt(3)
	v_lshlrev_b32_e32 v48, 16, v221
	s_waitcnt vmcnt(2)
	v_lshlrev_b32_e32 v49, 16, v222
	v_add_f32_e32 v48, v45, v48
	s_waitcnt vmcnt(1)
	v_lshlrev_b32_e32 v50, 16, v223
	v_add_f32_e32 v48, v48, v49
	s_waitcnt vmcnt(0)
	v_lshlrev_b32_e32 v51, 16, v224
	v_add_f32_e32 v48, v48, v50
	v_add_f32_e32 v48, v48, v51
	v_mul_f32_e32 v49, 0x3d372713, v48
	v_mul_f32_e32 v49, v48, v49
	v_fma_f32 v49, v48, v49, v48
	v_mul_f32_e32 v49, 0x3f4c422a, v49
	v_cmp_nlt_f32_e64 s[4:5], |v49|, s4
	s_and_saveexec_b64 s[12:13], s[4:5]
	s_xor_b64 s[12:13], exec, s[12:13]
	s_cbranch_execz .LBB0_1145
	v_add_f32_e64 v50, |v49|, |v49|
	v_mul_f32_e32 v51, 0x3fb8aa3b, v50
	s_mov_b32 s4, 0x3fb8aa3b
	v_rndne_f32_e32 v52, v51
	v_sub_f32_e32 v53, v51, v52
	v_fma_f32 v51, v50, s4, -v51
	v_fmamk_f32 v51, v50, 0x32a5705f, v51
	v_add_f32_e32 v51, v53, v51
	v_exp_f32_e32 v51, v51
	v_cvt_i32_f32_e32 v52, v52
	s_mov_b32 s4, 0xc2ce8ed0
	v_cmp_ngt_f32_e32 vcc, s4, v50
	s_mov_b32 s4, 0x42b17218
	v_ldexp_f32 v51, v51, v52
	v_cndmask_b32_e32 v51, 0, v51, vcc
	v_mov_b32_e32 v52, 0x7f800000
	v_cmp_nlt_f32_e32 vcc, s4, v50
	s_nop 1
	v_cndmask_b32_e32 v50, v52, v51, vcc
	v_add_f32_e32 v50, 1.0, v50
	v_rcp_f32_e32 v50, v50
	s_nop 0
	v_fma_f32 v50, v50, -2.0, 1.0
.LBB0_1145:
	s_andn2_saveexec_b64 s[12:13], s[12:13]
	v_mul_f32_e32 v50, v49, v49
	v_mov_b32_e32 v51, 0x3ca908c9
	v_fmac_f32_e32 v51, 0xbbbac73d, v50
	v_fmaak_f32 v51, v50, v51, 0xbd5c1c4e
	v_fmaak_f32 v51, v50, v51, 0x3e088382
	v_fmaak_f32 v51, v50, v51, 0xbeaaaa99
	v_mul_f32_e64 v51, |v49|, v51
	v_fma_f32 v50, v50, v51, |v49|
	s_or_b64 exec, exec, s[12:13]
	s_brev_b32 s4, -2
	v_bfi_b32 v49, s4, v50, v49
	v_mul_f32_e32 v48, 0.5, v48
	v_add_f32_e32 v49, 1.0, v49
	v_mul_f32_e32 v48, v48, v49
	ds_write_b32 v39, v48 offset:2304
	s_mov_b32 s4, 0x3f200000
	s_waitcnt vmcnt(3)
	v_lshlrev_b32_e32 v48, 16, v225
	s_waitcnt vmcnt(2)
	v_lshlrev_b32_e32 v49, 16, v226
	v_add_f32_e32 v48, v46, v48
	s_waitcnt vmcnt(1)
	v_lshlrev_b32_e32 v50, 16, v227
	v_add_f32_e32 v48, v48, v49
	s_waitcnt vmcnt(0)
	v_lshlrev_b32_e32 v51, 16, v228
	v_add_f32_e32 v48, v48, v50
	v_add_f32_e32 v48, v48, v51
	v_mul_f32_e32 v49, 0x3d372713, v48
	v_mul_f32_e32 v49, v48, v49
	v_fma_f32 v49, v48, v49, v48
	v_mul_f32_e32 v49, 0x3f4c422a, v49
	v_cmp_nlt_f32_e64 s[4:5], |v49|, s4
	s_and_saveexec_b64 s[12:13], s[4:5]
	s_xor_b64 s[12:13], exec, s[12:13]
	s_cbranch_execz .LBB0_1149
	v_add_f32_e64 v50, |v49|, |v49|
	v_mul_f32_e32 v51, 0x3fb8aa3b, v50
	s_mov_b32 s4, 0x3fb8aa3b
	v_rndne_f32_e32 v52, v51
	v_sub_f32_e32 v53, v51, v52
	v_fma_f32 v51, v50, s4, -v51
	v_fmamk_f32 v51, v50, 0x32a5705f, v51
	v_add_f32_e32 v51, v53, v51
	v_exp_f32_e32 v51, v51
	v_cvt_i32_f32_e32 v52, v52
	s_mov_b32 s4, 0xc2ce8ed0
	v_cmp_ngt_f32_e32 vcc, s4, v50
	s_mov_b32 s4, 0x42b17218
	v_ldexp_f32 v51, v51, v52
	v_cndmask_b32_e32 v51, 0, v51, vcc
	v_mov_b32_e32 v52, 0x7f800000
	v_cmp_nlt_f32_e32 vcc, s4, v50
	s_nop 1
	v_cndmask_b32_e32 v50, v52, v51, vcc
	v_add_f32_e32 v50, 1.0, v50
	v_rcp_f32_e32 v50, v50
	s_nop 0
	v_fma_f32 v50, v50, -2.0, 1.0
.LBB0_1149:
	s_andn2_saveexec_b64 s[12:13], s[12:13]
	v_mul_f32_e32 v50, v49, v49
	v_mov_b32_e32 v51, 0x3ca908c9
	v_fmac_f32_e32 v51, 0xbbbac73d, v50
	v_fmaak_f32 v51, v50, v51, 0xbd5c1c4e
	v_fmaak_f32 v51, v50, v51, 0x3e088382
	v_fmaak_f32 v51, v50, v51, 0xbeaaaa99
	v_mul_f32_e64 v51, |v49|, v51
	v_fma_f32 v50, v50, v51, |v49|
	s_or_b64 exec, exec, s[12:13]
	s_brev_b32 s4, -2
	v_bfi_b32 v49, s4, v50, v49
	v_mul_f32_e32 v48, 0.5, v48
	v_add_f32_e32 v49, 1.0, v49
	v_mul_f32_e32 v48, v48, v49
	ds_write_b32 v39, v48 offset:2560
	s_mov_b32 s4, 0x3f200000
	s_waitcnt vmcnt(3)
	v_lshlrev_b32_e32 v48, 16, v229
	s_waitcnt vmcnt(2)
	v_lshlrev_b32_e32 v49, 16, v230
	v_add_f32_e32 v48, v47, v48
	s_waitcnt vmcnt(1)
	v_lshlrev_b32_e32 v50, 16, v231
	v_add_f32_e32 v48, v48, v49
	s_waitcnt vmcnt(0)
	v_lshlrev_b32_e32 v51, 16, v232
	v_add_f32_e32 v48, v48, v50
	v_add_f32_e32 v48, v48, v51
	v_mul_f32_e32 v49, 0x3d372713, v48
	v_mul_f32_e32 v49, v48, v49
	v_fma_f32 v49, v48, v49, v48
	v_mul_f32_e32 v49, 0x3f4c422a, v49
	v_cmp_nlt_f32_e64 s[4:5], |v49|, s4
	s_and_saveexec_b64 s[12:13], s[4:5]
	s_xor_b64 s[12:13], exec, s[12:13]
	s_cbranch_execz .LBB0_1153
	v_add_f32_e64 v50, |v49|, |v49|
	v_mul_f32_e32 v51, 0x3fb8aa3b, v50
	s_mov_b32 s4, 0x3fb8aa3b
	v_rndne_f32_e32 v52, v51
	v_sub_f32_e32 v53, v51, v52
	v_fma_f32 v51, v50, s4, -v51
	v_fmamk_f32 v51, v50, 0x32a5705f, v51
	v_add_f32_e32 v51, v53, v51
	v_exp_f32_e32 v51, v51
	v_cvt_i32_f32_e32 v52, v52
	s_mov_b32 s4, 0xc2ce8ed0
	v_cmp_ngt_f32_e32 vcc, s4, v50
	s_mov_b32 s4, 0x42b17218
	v_ldexp_f32 v51, v51, v52
	v_cndmask_b32_e32 v51, 0, v51, vcc
	v_mov_b32_e32 v52, 0x7f800000
	v_cmp_nlt_f32_e32 vcc, s4, v50
	s_nop 1
	v_cndmask_b32_e32 v50, v52, v51, vcc
	v_add_f32_e32 v50, 1.0, v50
	v_rcp_f32_e32 v50, v50
	s_nop 0
	v_fma_f32 v50, v50, -2.0, 1.0
.LBB0_1153:
	s_andn2_saveexec_b64 s[12:13], s[12:13]
	v_mul_f32_e32 v50, v49, v49
	v_mov_b32_e32 v51, 0x3ca908c9
	v_fmac_f32_e32 v51, 0xbbbac73d, v50
	v_fmaak_f32 v51, v50, v51, 0xbd5c1c4e
	v_fmaak_f32 v51, v50, v51, 0x3e088382
	v_fmaak_f32 v51, v50, v51, 0xbeaaaa99
	v_mul_f32_e64 v51, |v49|, v51
	v_fma_f32 v50, v50, v51, |v49|
	s_or_b64 exec, exec, s[12:13]
	s_brev_b32 s4, -2
	v_bfi_b32 v49, s4, v50, v49
	v_mul_f32_e32 v48, 0.5, v48
	v_add_f32_e32 v49, 1.0, v49
	v_mul_f32_e32 v48, v48, v49
	ds_write_b32 v39, v48 offset:2816
	s_mov_b32 s4, 0x3f200000
	s_waitcnt vmcnt(3)
	v_lshlrev_b32_e32 v48, 16, v233
	s_waitcnt vmcnt(2)
	v_lshlrev_b32_e32 v49, 16, v234
	v_add_f32_e32 v44, v44, v48
	s_waitcnt vmcnt(1)
	v_lshlrev_b32_e32 v50, 16, v235
	v_add_f32_e32 v44, v44, v49
	s_waitcnt vmcnt(0)
	v_lshlrev_b32_e32 v51, 16, v236
	v_add_f32_e32 v44, v44, v50
	v_add_f32_e32 v44, v44, v51
	v_mul_f32_e32 v48, 0x3d372713, v44
	v_mul_f32_e32 v48, v44, v48
	v_fma_f32 v48, v44, v48, v44
	v_mul_f32_e32 v48, 0x3f4c422a, v48
	v_cmp_nlt_f32_e64 s[4:5], |v48|, s4
	s_and_saveexec_b64 s[12:13], s[4:5]
	s_xor_b64 s[12:13], exec, s[12:13]
	s_cbranch_execz .LBB0_1157
	v_add_f32_e64 v49, |v48|, |v48|
	v_mul_f32_e32 v50, 0x3fb8aa3b, v49
	s_mov_b32 s4, 0x3fb8aa3b
	v_rndne_f32_e32 v51, v50
	v_sub_f32_e32 v52, v50, v51
	v_fma_f32 v50, v49, s4, -v50
	v_fmamk_f32 v50, v49, 0x32a5705f, v50
	v_add_f32_e32 v50, v52, v50
	v_exp_f32_e32 v50, v50
	v_cvt_i32_f32_e32 v51, v51
	s_mov_b32 s4, 0xc2ce8ed0
	v_cmp_ngt_f32_e32 vcc, s4, v49
	s_mov_b32 s4, 0x42b17218
	v_ldexp_f32 v50, v50, v51
	v_cndmask_b32_e32 v50, 0, v50, vcc
	v_mov_b32_e32 v51, 0x7f800000
	v_cmp_nlt_f32_e32 vcc, s4, v49
	s_nop 1
	v_cndmask_b32_e32 v49, v51, v50, vcc
	v_add_f32_e32 v49, 1.0, v49
	v_rcp_f32_e32 v49, v49
	s_nop 0
	v_fma_f32 v49, v49, -2.0, 1.0
.LBB0_1157:
	s_andn2_saveexec_b64 s[12:13], s[12:13]
	v_mul_f32_e32 v49, v48, v48
	v_mov_b32_e32 v50, 0x3ca908c9
	v_fmac_f32_e32 v50, 0xbbbac73d, v49
	v_fmaak_f32 v50, v49, v50, 0xbd5c1c4e
	v_fmaak_f32 v50, v49, v50, 0x3e088382
	v_fmaak_f32 v50, v49, v50, 0xbeaaaa99
	v_mul_f32_e64 v50, |v48|, v50
	v_fma_f32 v49, v49, v50, |v48|
	s_or_b64 exec, exec, s[12:13]
	s_brev_b32 s4, -2
	v_bfi_b32 v48, s4, v49, v48
	v_mul_f32_e32 v44, 0.5, v44
	v_add_f32_e32 v48, 1.0, v48
	v_mul_f32_e32 v44, v44, v48
	ds_write_b32 v39, v44 offset:3072
	s_mov_b32 s4, 0x3f200000
	s_waitcnt vmcnt(3)
	v_lshlrev_b32_e32 v44, 16, v237
	s_waitcnt vmcnt(2)
	v_lshlrev_b32_e32 v48, 16, v238
	v_add_f32_e32 v44, v45, v44
	s_waitcnt vmcnt(1)
	v_lshlrev_b32_e32 v49, 16, v239
	v_add_f32_e32 v44, v44, v48
	s_waitcnt vmcnt(0)
	v_lshlrev_b32_e32 v50, 16, v240
	v_add_f32_e32 v44, v44, v49
	v_add_f32_e32 v44, v44, v50
	v_mul_f32_e32 v45, 0x3d372713, v44
	v_mul_f32_e32 v45, v44, v45
	v_fma_f32 v45, v44, v45, v44
	v_mul_f32_e32 v45, 0x3f4c422a, v45
	v_cmp_nlt_f32_e64 s[4:5], |v45|, s4
	s_and_saveexec_b64 s[12:13], s[4:5]
	s_xor_b64 s[12:13], exec, s[12:13]
	s_cbranch_execz .LBB0_1161
	v_add_f32_e64 v48, |v45|, |v45|
	v_mul_f32_e32 v49, 0x3fb8aa3b, v48
	s_mov_b32 s4, 0x3fb8aa3b
	v_rndne_f32_e32 v50, v49
	v_sub_f32_e32 v51, v49, v50
	v_fma_f32 v49, v48, s4, -v49
	v_fmamk_f32 v49, v48, 0x32a5705f, v49
	v_add_f32_e32 v49, v51, v49
	v_exp_f32_e32 v49, v49
	v_cvt_i32_f32_e32 v50, v50
	s_mov_b32 s4, 0xc2ce8ed0
	v_cmp_ngt_f32_e32 vcc, s4, v48
	s_mov_b32 s4, 0x42b17218
	v_ldexp_f32 v49, v49, v50
	v_cndmask_b32_e32 v49, 0, v49, vcc
	v_mov_b32_e32 v50, 0x7f800000
	v_cmp_nlt_f32_e32 vcc, s4, v48
	s_nop 1
	v_cndmask_b32_e32 v48, v50, v49, vcc
	v_add_f32_e32 v48, 1.0, v48
	v_rcp_f32_e32 v48, v48
	s_nop 0
	v_fma_f32 v48, v48, -2.0, 1.0
.LBB0_1161:
	s_andn2_saveexec_b64 s[12:13], s[12:13]
	v_mul_f32_e32 v48, v45, v45
	v_mov_b32_e32 v49, 0x3ca908c9
	v_fmac_f32_e32 v49, 0xbbbac73d, v48
	v_fmaak_f32 v49, v48, v49, 0xbd5c1c4e
	v_fmaak_f32 v49, v48, v49, 0x3e088382
	v_fmaak_f32 v49, v48, v49, 0xbeaaaa99
	v_mul_f32_e64 v49, |v45|, v49
	v_fma_f32 v48, v48, v49, |v45|
	s_or_b64 exec, exec, s[12:13]
	s_brev_b32 s4, -2
	v_bfi_b32 v45, s4, v48, v45
	v_mul_f32_e32 v44, 0.5, v44
	v_add_f32_e32 v45, 1.0, v45
	v_mul_f32_e32 v44, v44, v45
	ds_write_b32 v39, v44 offset:3328
	s_mov_b32 s4, 0x3f200000
	s_waitcnt vmcnt(3)
	v_lshlrev_b32_e32 v44, 16, v241
	s_waitcnt vmcnt(2)
	v_lshlrev_b32_e32 v45, 16, v242
	v_add_f32_e32 v44, v46, v44
	s_waitcnt vmcnt(1)
	v_lshlrev_b32_e32 v48, 16, v243
	v_add_f32_e32 v44, v44, v45
	s_waitcnt vmcnt(0)
	v_lshlrev_b32_e32 v49, 16, v244
	v_add_f32_e32 v44, v44, v48
	v_add_f32_e32 v44, v44, v49
	v_mul_f32_e32 v45, 0x3d372713, v44
	v_mul_f32_e32 v45, v44, v45
	v_fma_f32 v45, v44, v45, v44
	v_mul_f32_e32 v45, 0x3f4c422a, v45
	v_cmp_nlt_f32_e64 s[4:5], |v45|, s4
	s_and_saveexec_b64 s[12:13], s[4:5]
	s_xor_b64 s[12:13], exec, s[12:13]
	s_cbranch_execz .LBB0_1165
	v_add_f32_e64 v46, |v45|, |v45|
	v_mul_f32_e32 v48, 0x3fb8aa3b, v46
	s_mov_b32 s4, 0x3fb8aa3b
	v_rndne_f32_e32 v49, v48
	v_sub_f32_e32 v50, v48, v49
	v_fma_f32 v48, v46, s4, -v48
	v_fmamk_f32 v48, v46, 0x32a5705f, v48
	v_add_f32_e32 v48, v50, v48
	v_exp_f32_e32 v48, v48
	v_cvt_i32_f32_e32 v49, v49
	s_mov_b32 s4, 0xc2ce8ed0
	v_cmp_ngt_f32_e32 vcc, s4, v46
	s_mov_b32 s4, 0x42b17218
	v_ldexp_f32 v48, v48, v49
	v_cndmask_b32_e32 v48, 0, v48, vcc
	v_mov_b32_e32 v49, 0x7f800000
	v_cmp_nlt_f32_e32 vcc, s4, v46
	s_nop 1
	v_cndmask_b32_e32 v46, v49, v48, vcc
	v_add_f32_e32 v46, 1.0, v46
	v_rcp_f32_e32 v46, v46
	s_nop 0
	v_fma_f32 v46, v46, -2.0, 1.0
.LBB0_1165:
	s_andn2_saveexec_b64 s[12:13], s[12:13]
	v_mul_f32_e32 v46, v45, v45
	v_mov_b32_e32 v48, 0x3ca908c9
	v_fmac_f32_e32 v48, 0xbbbac73d, v46
	v_fmaak_f32 v48, v46, v48, 0xbd5c1c4e
	v_fmaak_f32 v48, v46, v48, 0x3e088382
	v_fmaak_f32 v48, v46, v48, 0xbeaaaa99
	v_mul_f32_e64 v48, |v45|, v48
	v_fma_f32 v46, v46, v48, |v45|
	s_or_b64 exec, exec, s[12:13]
	s_brev_b32 s4, -2
	v_bfi_b32 v35, s4, v46, v45
	v_mul_f32_e32 v34, 0.5, v44
	v_add_f32_e32 v35, 1.0, v35
	v_mul_f32_e32 v34, v34, v35
	ds_write_b32 v39, v34 offset:3584
	s_mov_b32 s4, 0x3f200000
	s_waitcnt vmcnt(3)
	v_lshlrev_b32_e32 v34, 16, v245
	s_waitcnt vmcnt(2)
	v_lshlrev_b32_e32 v35, 16, v246
	v_add_f32_e32 v34, v47, v34
	s_waitcnt vmcnt(1)
	v_lshlrev_b32_e32 v36, 16, v247
	v_add_f32_e32 v34, v34, v35
	s_waitcnt vmcnt(0)
	v_lshlrev_b32_e32 v37, 16, v248
	v_add_f32_e32 v34, v34, v36
	v_add_f32_e32 v34, v34, v37
	v_mul_f32_e32 v35, 0x3d372713, v34
	v_mul_f32_e32 v35, v34, v35
	v_fma_f32 v35, v34, v35, v34
	v_mul_f32_e32 v35, 0x3f4c422a, v35
	v_cmp_nlt_f32_e64 s[4:5], |v35|, s4
	s_and_saveexec_b64 s[12:13], s[4:5]
	s_xor_b64 s[12:13], exec, s[12:13]
	s_cbranch_execz .LBB0_1169
	v_add_f32_e64 v36, |v35|, |v35|
	v_mul_f32_e32 v37, 0x3fb8aa3b, v36
	s_mov_b32 s4, 0x3fb8aa3b
	v_rndne_f32_e32 v40, v37
	v_sub_f32_e32 v41, v37, v40
	v_fma_f32 v37, v36, s4, -v37
	v_fmamk_f32 v37, v36, 0x32a5705f, v37
	v_add_f32_e32 v37, v41, v37
	v_exp_f32_e32 v37, v37
	v_cvt_i32_f32_e32 v40, v40
	s_mov_b32 s4, 0xc2ce8ed0
	v_cmp_ngt_f32_e32 vcc, s4, v36
	s_mov_b32 s4, 0x42b17218
	v_ldexp_f32 v37, v37, v40
	v_cndmask_b32_e32 v37, 0, v37, vcc
	v_mov_b32_e32 v40, 0x7f800000
	v_cmp_nlt_f32_e32 vcc, s4, v36
	s_nop 1
	v_cndmask_b32_e32 v36, v40, v37, vcc
	v_add_f32_e32 v36, 1.0, v36
	v_rcp_f32_e32 v36, v36
	s_nop 0
	v_fma_f32 v36, v36, -2.0, 1.0
